# speedup vs baseline: 1.0153x; 1.0153x over previous
; #define PEER_NEXTOPS(t_) do { const u32x4* xr_ = (const u32x4*)(xb + (size_t)(t_) * PA + 32 * l5); xq[0] = xr_[0]; xq[1] = xr_[1]; xq[2] = xr_[2]; xq[3] = xr_[3]; \
;         ivq0 = eidx[(size_t)(t_) * 128 + lane]; ivq1 = eidx[(size_t)(t_) * 128 + 64 + lane]; gvq0 = gate[(size_t)(t_) * 128 + lane]; gvq1 = gate[(size_t)(t_) * 128 + 64 + lane]; } while (0)
; DI void peer_phase(const Params& p, int layer, bool dry) {
;     ...
;         float fh[16];
; #pragma unroll
;         for (int i = 0; i < 8; ++i) {
;             const float s0 = f2[i].x + __shfl_xor(f2[i].x, 32), s1 = f2[i].y + __shfl_xor(f2[i].y, 32);
;             const float s2 = f2[8 + i].x + __shfl_xor(f2[8 + i].x, 32), s3 = f2[8 + i].y + __shfl_xor(f2[8 + i].y, 32);
;             fh[2 * i] = hi ? s2 : s0; fh[2 * i + 1] = hi ? s3 : s1;
;         }
;         const int cb = 32 * l5 + 16 * hi;
;         float hv[16]; float s = 0.f;
; #pragma unroll
;         for (int i = 0; i < 8; ++i) {
;             const float xa = hi ? x2[8 + i].x : x2[i].x, xc = hi ? x2[8 + i].y : x2[i].y;
;             hv[2 * i] = ALPHA * xa + fh[2 * i]; hv[2 * i + 1] = ALPHA * xc + fh[2 * i + 1];
;             s += hv[2 * i] + hv[2 * i + 1];
;         }
;         PEER_NEXTOPS(tn);
;         const float mean = wave_sum(s) * (1.f / DM); float qv = 0.f;
; #pragma unroll
;         for (int i = 0; i < 16; ++i) { hv[i] -= mean; qv += hv[i] * hv[i]; }
;         const float rstd = rsqrtf(wave_sum(qv) * (1.f / DM) + LN_EPS);
;         float* orow = p.out + (size_t)t * DM + cb;
;         float ov[16];
; #pragma unroll
;         for (int c = 0; c < 4; ++c) {
;             const f32x4 gg = *(const f32x4*)(g2 + cb + 4 * c), bb = *(const f32x4*)(b2 + cb + 4 * c);
;             f32x4 o; o.x = hv[4 * c] * rstd * gg.x + bb.x; o.y = hv[4 * c + 1] * rstd * gg.y + bb.y; o.z = hv[4 * c + 2] * rstd * gg.z + bb.z; o.w = hv[4 * c + 3] * rstd * gg.w + bb.w;
;             if (!dry && layer == 1) *(f32x4*)(orow + 4 * c) = o;
.LBB0_40:
	s_nop 1
	v_permlane32_swap_b32_e32 v186, v160
	v_permlane32_swap_b32_e32 v187, v161
	v_permlane32_swap_b32_e32 v184, v182
	v_permlane32_swap_b32_e32 v185, v183
	v_permlane32_swap_b32_e32 v164, v162
	v_permlane32_swap_b32_e32 v165, v163
	v_permlane32_swap_b32_e32 v180, v178
	v_permlane32_swap_b32_e32 v181, v179
	v_permlane32_swap_b32_e32 v168, v166
	v_permlane32_swap_b32_e32 v169, v167
	v_permlane32_swap_b32_e32 v176, v174
	v_permlane32_swap_b32_e32 v177, v175
	v_permlane32_swap_b32_e32 v172, v170
	v_permlane32_swap_b32_e32 v173, v171
	v_permlane32_swap_b32_e32 v188, v158
	v_permlane32_swap_b32_e32 v189, v159
	v_pk_add_f32 v[92:93], v[186:187], v[160:161]
	v_pk_add_f32 v[88:89], v[184:185], v[182:183]
	v_pk_add_f32 v[64:65], v[188:189], v[158:159]
	v_cndmask_b32_e64 v113, v115, v113, s[8:9]
	v_cndmask_b32_e64 v112, v114, v112, s[8:9]
	v_cndmask_b32_e64 v115, v119, v117, s[8:9]
	v_cndmask_b32_e64 v114, v118, v116, s[8:9]
	v_cndmask_b32_e64 v119, v127, v125, s[8:9]
	v_cndmask_b32_e64 v118, v126, v124, s[8:9]
	v_cndmask_b32_e64 v125, v153, v151, s[8:9]
	v_cndmask_b32_e64 v124, v152, v150, s[8:9]
	v_cndmask_b32_e64 v127, v157, v155, s[8:9]
	v_cndmask_b32_e64 v126, v156, v154, s[8:9]
	v_pk_add_f32 v[68:69], v[164:165], v[162:163]
	v_pk_fma_f32 v[94:95], v[126:127], s[78:79], v[92:93] op_sel_hi:[1,0,1]
	v_pk_fma_f32 v[92:93], v[124:125], s[78:79], v[88:89] op_sel_hi:[1,0,1]
	v_pk_add_f32 v[84:85], v[180:181], v[178:179]
	v_pk_add_f32 v[72:73], v[168:169], v[166:167]
	v_pk_fma_f32 v[112:113], v[112:113], s[78:79], v[64:65] op_sel_hi:[1,0,1]
	v_cndmask_b32_e64 v117, v123, v121, s[8:9]
	v_cndmask_b32_e64 v116, v122, v120, s[8:9]
	v_cndmask_b32_e64 v123, v149, v147, s[8:9]
	v_cndmask_b32_e64 v122, v148, v146, s[8:9]
	v_mov_b32_e32 v88, v92
	v_mov_b32_e32 v89, v94
	v_mov_b32_e32 v90, v93
	v_mov_b32_e32 v91, v95
	v_pk_add_f32 v[80:81], v[176:177], v[174:175]
	v_pk_add_f32 v[76:77], v[172:173], v[170:171]
	v_pk_fma_f32 v[114:115], v[114:115], s[78:79], v[68:69] op_sel_hi:[1,0,1]
	v_add_f32_e32 v64, v112, v113
	v_cndmask_b32_e64 v121, v145, v143, s[8:9]
	v_cndmask_b32_e64 v120, v144, v142, s[8:9]
	v_pk_add_f32 v[88:89], v[88:89], v[90:91]
	v_pk_fma_f32 v[90:91], v[122:123], s[78:79], v[84:85] op_sel_hi:[1,0,1]
	v_pk_fma_f32 v[84:85], v[116:117], s[78:79], v[72:73] op_sel_hi:[1,0,1]
	v_add_f32_e32 v68, v114, v115
	v_add_f32_e32 v64, 0, v64
	v_pk_fma_f32 v[120:121], v[120:121], s[78:79], v[80:81] op_sel_hi:[1,0,1]
	v_pk_fma_f32 v[86:87], v[118:119], s[78:79], v[76:77] op_sel_hi:[1,0,1]
	v_add_f32_e32 v72, v84, v85
	v_add_f32_e32 v64, v64, v68
	v_mov_b32_e32 v80, v120
	v_mov_b32_e32 v81, v90
	v_mov_b32_e32 v82, v121
	v_mov_b32_e32 v83, v91
	v_add_f32_e32 v76, v86, v87
	v_add_f32_e32 v64, v64, v72
	v_pk_add_f32 v[80:81], v[80:81], v[82:83]
	v_add_f32_e32 v64, v64, v76
	v_add_f32_e32 v64, v64, v80
	v_add_f32_e32 v64, v64, v81
	v_add_f32_e32 v64, v64, v88
	v_add_f32_e32 v64, v64, v89
	s_nop 1
	v_add_f32_dpp v80, v64, v64 quad_perm:[1,0,3,2] row_mask:0xf bank_mask:0xf
	s_lshl_b64 s[22:23], s[22:23], 11
	v_lshl_add_u64 v[76:77], v[100:101], 0, s[22:23]
	s_ashr_i32 s21, s20, 31
	global_load_dwordx4 v[64:67], v[76:77], off offset:48
	global_load_dwordx4 v[72:75], v[76:77], off offset:32
	global_load_dwordx4 v[68:71], v[76:77], off offset:16
	s_nop 0
	global_load_dwordx4 v[76:79], v[76:77], off
	s_lshl_b64 s[0:1], s[20:21], 12
	s_nop 1
	v_add_f32_dpp v80, v80, v80 quad_perm:[2,3,0,1] row_mask:0xf bank_mask:0xf
	s_nop 1
	v_add_f32_dpp v80, v80, v80 row_half_mirror row_mask:0xf bank_mask:0xf
	s_nop 1
	v_add_f32_dpp v80, v80, v80 row_mirror row_mask:0xf bank_mask:0xf
	s_nop 1
	v_add_f32_dpp v80, v80, v80 row_bcast:15 row_mask:0xa bank_mask:0xf
	s_nop 1
	v_add_f32_dpp v80, v80, v80 row_bcast:31 row_mask:0xc bank_mask:0xf
	s_nop 0
	v_readlane_b32 s44, v80, 63
	s_nop 1
	v_mov_b32_e32 v88, s44
	v_mul_f32_e32 v122, 0x3a800000, v88
	v_pk_add_f32 v[124:125], v[112:113], v[122:123] op_sel_hi:[1,0] neg_lo:[0,1] neg_hi:[0,1]
	v_pk_add_f32 v[126:127], v[114:115], v[122:123] op_sel_hi:[1,0] neg_lo:[0,1] neg_hi:[0,1]
	v_pk_mul_f32 v[112:113], v[124:125], v[124:125]
	v_pk_mul_f32 v[114:115], v[126:127], v[126:127]
	v_add_f32_e32 v112, v112, v113
	v_pk_add_f32 v[84:85], v[84:85], v[122:123] op_sel_hi:[1,0] neg_lo:[0,1] neg_hi:[0,1]
	v_add_f32_e32 v112, v114, v112
	v_pk_mul_f32 v[142:143], v[84:85], v[84:85]
	v_add_f32_e32 v112, v115, v112
	v_pk_add_f32 v[86:87], v[86:87], v[122:123] op_sel_hi:[1,0] neg_lo:[0,1] neg_hi:[0,1]
	v_add_f32_e32 v112, v142, v112
	v_pk_mul_f32 v[144:145], v[86:87], v[86:87]
	v_add_f32_e32 v112, v143, v112
	v_pk_add_f32 v[88:89], v[120:121], v[122:123] op_sel_hi:[1,0] neg_lo:[0,1] neg_hi:[0,1]
	v_add_f32_e32 v112, v144, v112
	v_pk_mul_f32 v[120:121], v[88:89], v[88:89]
	v_add_f32_e32 v112, v145, v112
	v_pk_add_f32 v[90:91], v[90:91], v[122:123] op_sel_hi:[1,0] neg_lo:[0,1] neg_hi:[0,1]
	v_add_f32_e32 v112, v120, v112
	v_pk_mul_f32 v[146:147], v[90:91], v[90:91]
	v_add_f32_e32 v112, v121, v112
	v_pk_add_f32 v[92:93], v[92:93], v[122:123] op_sel_hi:[1,0] neg_lo:[0,1] neg_hi:[0,1]
	v_add_f32_e32 v112, v146, v112
	v_pk_mul_f32 v[148:149], v[92:93], v[92:93]
	v_add_f32_e32 v112, v147, v112
	v_pk_add_f32 v[94:95], v[94:95], v[122:123] op_sel_hi:[1,0] neg_lo:[0,1] neg_hi:[0,1]
	v_add_f32_e32 v112, v148, v112
	v_pk_mul_f32 v[122:123], v[94:95], v[94:95]
	v_add_f32_e32 v112, v149, v112
	v_add_f32_e32 v112, v122, v112
	v_add_f32_e32 v112, v123, v112
	s_nop 1
	v_add_f32_dpp v112, v112, v112 quad_perm:[1,0,3,2] row_mask:0xf bank_mask:0xf
	s_nop 1
	v_add_f32_dpp v112, v112, v112 quad_perm:[2,3,0,1] row_mask:0xf bank_mask:0xf
	s_nop 1
	v_add_f32_dpp v112, v112, v112 row_half_mirror row_mask:0xf bank_mask:0xf
	s_nop 1
	v_add_f32_dpp v112, v112, v112 row_mirror row_mask:0xf bank_mask:0xf
	s_nop 1
	v_add_f32_dpp v112, v112, v112 row_bcast:15 row_mask:0xa bank_mask:0xf
	s_nop 1
	v_add_f32_dpp v112, v112, v112 row_bcast:31 row_mask:0xc bank_mask:0xf
	s_nop 0
	v_readlane_b32 s44, v112, 63
	s_nop 1
	v_mov_b32_e32 v112, s44
	v_fmamk_f32 v112, v112, 0x3a800000, v195
	v_mul_f32_e32 v113, 0x4b800000, v112
	v_cmp_gt_f32_e32 vcc, s69, v112
	s_nop 1
	v_cndmask_b32_e32 v112, v112, v113, vcc
	v_rsq_f32_e32 v114, v112
	v_lshl_add_u64 v[112:113], v[110:111], 0, s[0:1]
	v_mul_f32_e32 v115, 0x45800000, v114
	v_cndmask_b32_e32 v114, v114, v115, vcc
	v_pk_mul_f32 v[120:121], v[124:125], v[114:115] op_sel_hi:[1,0]
	s_and_b64 vcc, exec, s[16:17]
	v_pk_fma_f32 v[80:81], v[234:235], v[120:121], v[130:131]
	v_pk_mul_f32 v[116:117], v[126:127], v[114:115] op_sel_hi:[1,0]
	s_nop 0
	v_pk_fma_f32 v[82:83], v[236:237], v[116:117], v[132:133]
	s_cbranch_vccz .LBB0_42
	global_store_dwordx4 v[112:113], v[80:83], off
